# chunk-state scan: the four state loads and four decay loads of each iteration issued together (one wait instead of eight)
# speedup vs baseline: 1.0072x; 1.0019x over previous
; __device__ __forceinline__ void st8(bf16_t* p, f32x4 a, f32x4 b) { u32x4 w; w.x = pk2(a[0], a[1]); w.y = pk2(a[2], a[3]); w.z = pk2(b[0], b[1]); w.w = pk2(b[2], b[3]); *(u32x4*)p = w; }
; __device__ __forceinline__ void ld8(const bf16_t* p, f32x4& a, f32x4& b) { const u32x4 w = *(const u32x4*)p; a[0] = bflo(w.x); a[1] = bfhi(w.x); a[2] = bflo(w.y); a[3] = bfhi(w.y); b[0] = bflo(w.z); b[1] = bfhi(w.z); b[2] = bflo(w.w); b[3] = bfhi(w.w); }
; __device__ __forceinline__ void ph_scan() {
;     ...
;     for (int e = bx * 512 + tid; e < NB * 32 * 1024; e += G * 512) {
;         const int bgh = e >> 10, pn8 = e & 1023, b = bgh >> 5, gh = bgh & 31;
;         f32x4 s0 = {0.f, 0.f, 0.f, 0.f}, s1 = {0.f, 0.f, 0.f, 0.f};
; #pragma unroll 4
;         for (int c = 0; c < 32; ++c) { const unsigned off = (unsigned)(((b * 32 + c) * 32 + gh) * 8192 + pn8 * 8);
;             f32x4 a0, a1; ld8(ST + off, a0, a1); st8(HP + off, s0, s1);
;             const float d = DEC[(b * 32 + c) * 32 + gh]; s0 = s0 * d + a0; s1 = s1 * d + a1; }
;     }
.LBB0_863:
	v_add_u32_e32 v0, 0xfff40000, v2
	v_lshlrev_b64 v[72:73], 1, v[0:1]
	v_add_u32_e32 v0, 0xfff80000, v2
	v_lshlrev_b64 v[74:75], 1, v[0:1]
	v_add_u32_e32 v0, 0xfffc0000, v2
	v_lshlrev_b64 v[76:77], 1, v[0:1]
	v_mov_b32_e32 v3, v1
	v_lshlrev_b64 v[78:79], 1, v[2:3]
	v_lshl_add_u64 v[68:69], s[6:7], 0, v[72:73]
	global_load_dwordx4 v[40:43], v[68:69], off
	v_lshl_add_u64 v[68:69], s[6:7], 0, v[74:75]
	global_load_dwordx4 v[44:47], v[68:69], off
	v_lshl_add_u64 v[68:69], s[6:7], 0, v[76:77]
	global_load_dwordx4 v[48:51], v[68:69], off
	v_lshl_add_u64 v[68:69], s[6:7], 0, v[78:79]
	global_load_dwordx4 v[56:59], v[68:69], off
	v_add_u32_e32 v4, s10, v16
	v_ashrrev_i32_e32 v5, 31, v4
	v_lshl_add_u64 v[68:69], v[4:5], 2, s[40:41]
	global_load_dword v60, v[68:69], off
	v_add_u32_e32 v70, 32, v4
	v_ashrrev_i32_e32 v71, 31, v70
	v_lshl_add_u64 v[68:69], v[70:71], 2, s[40:41]
	global_load_dword v62, v[68:69], off
	v_add_u32_e32 v70, 64, v4
	v_ashrrev_i32_e32 v71, 31, v70
	v_lshl_add_u64 v[68:69], v[70:71], 2, s[40:41]
	global_load_dword v64, v[68:69], off
	v_add_u32_e32 v70, 0x60, v4
	v_ashrrev_i32_e32 v71, 31, v70
	v_lshl_add_u64 v[68:69], v[70:71], 2, s[40:41]
	global_load_dword v66, v[68:69], off
	v_add_u32_e32 v2, 0x100000, v2
	s_addk_i32 s10, 0x80
	s_cmpk_eq_i32 s10, 0x400
	v_lshl_add_u64 v[72:73], s[38:39], 0, v[72:73]
	v_lshl_add_u64 v[74:75], s[38:39], 0, v[74:75]
	v_lshl_add_u64 v[76:77], s[38:39], 0, v[76:77]
	v_lshl_add_u64 v[78:79], s[38:39], 0, v[78:79]
	s_waitcnt vmcnt(0)
	v_cvt_pk_bf16_f32 v18, v10, v11
	v_cvt_pk_bf16_f32 v19, v12, v13
	v_cvt_pk_bf16_f32 v20, v6, v7
	v_cvt_pk_bf16_f32 v21, v8, v9
	global_store_dwordx4 v[72:73], v[18:21], off
	v_lshlrev_b32_e32 v24, 16, v40
	v_and_b32_e32 v25, 0xffff0000, v40
	v_lshlrev_b32_e32 v26, 16, v41
	v_and_b32_e32 v27, 0xffff0000, v41
	v_lshlrev_b32_e32 v28, 16, v42
	v_and_b32_e32 v29, 0xffff0000, v42
	v_lshlrev_b32_e32 v30, 16, v43
	v_and_b32_e32 v31, 0xffff0000, v43
	v_pk_fma_f32 v[10:11], v[10:11], v[60:61], v[24:25] op_sel_hi:[1,0,1]
	v_pk_fma_f32 v[12:13], v[12:13], v[60:61], v[26:27] op_sel_hi:[1,0,1]
	v_pk_fma_f32 v[6:7], v[6:7], v[60:61], v[28:29] op_sel_hi:[1,0,1]
	v_pk_fma_f32 v[8:9], v[8:9], v[60:61], v[30:31] op_sel_hi:[1,0,1]
	v_cvt_pk_bf16_f32 v18, v10, v11
	v_cvt_pk_bf16_f32 v19, v12, v13
	v_cvt_pk_bf16_f32 v20, v6, v7
	v_cvt_pk_bf16_f32 v21, v8, v9
	global_store_dwordx4 v[74:75], v[18:21], off
	v_lshlrev_b32_e32 v24, 16, v44
	v_and_b32_e32 v25, 0xffff0000, v44
	v_lshlrev_b32_e32 v26, 16, v45
	v_and_b32_e32 v27, 0xffff0000, v45
	v_lshlrev_b32_e32 v28, 16, v46
	v_and_b32_e32 v29, 0xffff0000, v46
	v_lshlrev_b32_e32 v30, 16, v47
	v_and_b32_e32 v31, 0xffff0000, v47
	v_pk_fma_f32 v[10:11], v[10:11], v[62:63], v[24:25] op_sel_hi:[1,0,1]
	v_pk_fma_f32 v[12:13], v[12:13], v[62:63], v[26:27] op_sel_hi:[1,0,1]
	v_pk_fma_f32 v[6:7], v[6:7], v[62:63], v[28:29] op_sel_hi:[1,0,1]
	v_pk_fma_f32 v[8:9], v[8:9], v[62:63], v[30:31] op_sel_hi:[1,0,1]
	v_cvt_pk_bf16_f32 v18, v10, v11
	v_cvt_pk_bf16_f32 v19, v12, v13
	v_cvt_pk_bf16_f32 v20, v6, v7
	v_cvt_pk_bf16_f32 v21, v8, v9
	global_store_dwordx4 v[76:77], v[18:21], off
	v_lshlrev_b32_e32 v24, 16, v48
	v_and_b32_e32 v25, 0xffff0000, v48
	v_lshlrev_b32_e32 v26, 16, v49
	v_and_b32_e32 v27, 0xffff0000, v49
	v_lshlrev_b32_e32 v28, 16, v50
	v_and_b32_e32 v29, 0xffff0000, v50
	v_lshlrev_b32_e32 v30, 16, v51
	v_and_b32_e32 v31, 0xffff0000, v51
	v_pk_fma_f32 v[10:11], v[10:11], v[64:65], v[24:25] op_sel_hi:[1,0,1]
	v_pk_fma_f32 v[12:13], v[12:13], v[64:65], v[26:27] op_sel_hi:[1,0,1]
	v_pk_fma_f32 v[6:7], v[6:7], v[64:65], v[28:29] op_sel_hi:[1,0,1]
	v_pk_fma_f32 v[8:9], v[8:9], v[64:65], v[30:31] op_sel_hi:[1,0,1]
	v_cvt_pk_bf16_f32 v18, v10, v11
	v_cvt_pk_bf16_f32 v19, v12, v13
	v_cvt_pk_bf16_f32 v20, v6, v7
	v_cvt_pk_bf16_f32 v21, v8, v9
	global_store_dwordx4 v[78:79], v[18:21], off
	v_lshlrev_b32_e32 v24, 16, v56
	v_and_b32_e32 v25, 0xffff0000, v56
	v_lshlrev_b32_e32 v26, 16, v57
	v_and_b32_e32 v27, 0xffff0000, v57
	v_lshlrev_b32_e32 v28, 16, v58
	v_and_b32_e32 v29, 0xffff0000, v58
	v_lshlrev_b32_e32 v30, 16, v59
	v_and_b32_e32 v31, 0xffff0000, v59
	v_pk_fma_f32 v[10:11], v[10:11], v[66:67], v[24:25] op_sel_hi:[1,0,1]
	v_pk_fma_f32 v[12:13], v[12:13], v[66:67], v[26:27] op_sel_hi:[1,0,1]
	v_pk_fma_f32 v[6:7], v[6:7], v[66:67], v[28:29] op_sel_hi:[1,0,1]
	v_pk_fma_f32 v[8:9], v[8:9], v[66:67], v[30:31] op_sel_hi:[1,0,1]
	s_cbranch_scc0 .LBB0_863
	v_add_u32_e32 v14, s8, v14
	s_mov_b32 s2, 0x1ffff
	v_cmp_lt_i32_e32 vcc, s2, v14
	s_or_b64 s[42:43], vcc, s[42:43]
	v_add_u32_e32 v15, s9, v15
	s_andn2_b64 exec, exec, s[42:43]
	s_cbranch_execnz .LBB0_862
